# gdn_prep q_dec stores re-indexed: thread part p handles columns 8p+32*c4 so each store instruction writes 64 contiguous bytes per row (half the cache lines touched)
# speedup vs baseline: 1.0205x; 1.0031x over previous
.LBB0_357:
	s_or_b64 exec, exec, s[44:45]
	v_cvt_pk_bf16_f32 v0, v0, v0
	global_store_short v[62:63], v0, off offset:224
	ds_read2st64_b32 v[0:1], v175 offset1:2
	s_add_u32 s44, s74, s28
	s_addc_u32 s45, s75, s29
	v_lshl_add_u64 v[16:17], s[44:45], 0, v[58:59]
	s_waitcnt lgkmcnt(0)
	v_mul_f32_e32 v0, 0x3fb8aa3b, v0
	v_exp_f32_e32 v0, v0
	s_nop 0
	v_mul_f32_e32 v18, v1, v0
	v_and_b32_e32 v110, 3, v160
	v_mul_u32_u24_e32 v110, 48, v110
	v_sub_u32_e32 v111, v184, v110
	v_sub_u32_e32 v114, 0, v110
	v_ashrrev_i32_e32 v115, 31, v114
	v_lshl_add_u64 v[112:113], v[16:17], 0, v[114:115]
	ds_read_b128 v[0:3], v111
	ds_read_b128 v[4:7], v111 offset:64
	ds_read_b128 v[8:11], v111 offset:128
	ds_read_b128 v[12:15], v111 offset:192
	s_waitcnt lgkmcnt(0)
	v_lshlrev_b32_e32 v19, 16, v0
	v_and_b32_e32 v0, 0xffff0000, v0
	v_lshlrev_b32_e32 v20, 16, v1
	v_and_b32_e32 v1, 0xffff0000, v1
	v_lshlrev_b32_e32 v22, 16, v3
	v_and_b32_e32 v3, 0xffff0000, v3
	v_lshlrev_b32_e32 v21, 16, v2
	v_and_b32_e32 v2, 0xffff0000, v2
	v_mul_f32_e32 v0, v18, v0
	v_mul_f32_e32 v1, v18, v1
	v_mul_f32_e32 v3, v18, v3
	v_mul_f32_e32 v19, v18, v19
	v_mul_f32_e32 v20, v18, v20
	v_mul_f32_e32 v2, v18, v2
	v_mul_f32_e32 v22, v18, v22
	v_cvt_pk_bf16_f32 v0, v19, v0
	v_cvt_pk_bf16_f32 v1, v20, v1
	v_cvt_pk_bf16_f32 v3, v22, v3
	v_mul_f32_e32 v21, v18, v21
	v_cvt_pk_bf16_f32 v2, v21, v2
	global_store_dwordx4 v[112:113], v[0:3], off offset:-32
	s_waitcnt lgkmcnt(2)
	s_nop 0
	v_lshlrev_b32_e32 v0, 16, v4
	v_and_b32_e32 v1, 0xffff0000, v4
	v_and_b32_e32 v3, 0xffff0000, v5
	v_lshlrev_b32_e32 v2, 16, v5
	v_lshlrev_b32_e32 v4, 16, v6
	v_and_b32_e32 v5, 0xffff0000, v6
	v_lshlrev_b32_e32 v6, 16, v7
	v_and_b32_e32 v7, 0xffff0000, v7
	v_mul_f32_e32 v0, v18, v0
	v_mul_f32_e32 v1, v18, v1
	v_mul_f32_e32 v3, v18, v3
	v_mul_f32_e32 v2, v18, v2
	v_mul_f32_e32 v6, v18, v6
	v_mul_f32_e32 v7, v18, v7
	v_cvt_pk_bf16_f32 v0, v0, v1
	v_cvt_pk_bf16_f32 v1, v2, v3
	v_cvt_pk_bf16_f32 v3, v6, v7
	v_mul_f32_e32 v4, v18, v4
	v_mul_f32_e32 v5, v18, v5
	v_cvt_pk_bf16_f32 v2, v4, v5
	global_store_dwordx4 v[112:113], v[0:3], off offset:32
	s_waitcnt lgkmcnt(1)
	v_lshlrev_b32_e32 v6, 16, v11
	v_and_b32_e32 v7, 0xffff0000, v11
	v_lshlrev_b32_e32 v0, 16, v8
	v_and_b32_e32 v1, 0xffff0000, v8
	v_and_b32_e32 v3, 0xffff0000, v9
	v_lshlrev_b32_e32 v2, 16, v9
	v_mul_f32_e32 v0, v18, v0
	v_mul_f32_e32 v1, v18, v1
	v_mul_f32_e32 v3, v18, v3
	v_lshlrev_b32_e32 v4, 16, v10
	v_and_b32_e32 v5, 0xffff0000, v10
	v_mul_f32_e32 v2, v18, v2
	v_mul_f32_e32 v6, v18, v6
	v_mul_f32_e32 v7, v18, v7
	v_cvt_pk_bf16_f32 v0, v0, v1
	v_cvt_pk_bf16_f32 v1, v2, v3
	v_cvt_pk_bf16_f32 v3, v6, v7
	v_mul_f32_e32 v4, v18, v4
	v_mul_f32_e32 v5, v18, v5
	v_cvt_pk_bf16_f32 v2, v4, v5
	global_store_dwordx4 v[112:113], v[0:3], off offset:96
	s_waitcnt lgkmcnt(0)
	v_lshlrev_b32_e32 v6, 16, v15
	v_and_b32_e32 v7, 0xffff0000, v15
	v_lshlrev_b32_e32 v0, 16, v12
	v_and_b32_e32 v1, 0xffff0000, v12
	v_and_b32_e32 v3, 0xffff0000, v13
	v_lshlrev_b32_e32 v2, 16, v13
	v_mul_f32_e32 v0, v18, v0
	v_mul_f32_e32 v1, v18, v1
	v_mul_f32_e32 v3, v18, v3
	v_lshlrev_b32_e32 v4, 16, v14
	v_and_b32_e32 v5, 0xffff0000, v14
	v_mul_f32_e32 v2, v18, v2
	v_mul_f32_e32 v6, v18, v6
	v_mul_f32_e32 v7, v18, v7
	v_cvt_pk_bf16_f32 v0, v0, v1
	v_cvt_pk_bf16_f32 v1, v2, v3
	v_cvt_pk_bf16_f32 v3, v6, v7
	v_mul_f32_e32 v4, v18, v4
	v_mul_f32_e32 v5, v18, v5
	v_cvt_pk_bf16_f32 v2, v4, v5
	global_store_dwordx4 v[112:113], v[0:3], off offset:160
	ds_read_u16 v3, v185
	ds_read_b32 v2, v168 offset:252
	ds_read2_b32 v[4:5], v181 offset0:192 offset1:193
	ds_read2_b32 v[6:7], v181 offset1:1
	v_lshl_add_u64 v[0:1], s[44:45], 0, v[60:61]
	s_waitcnt lgkmcnt(0)
	v_lshlrev_b32_e32 v3, 16, v3
	s_waitcnt lgkmcnt(1)
	v_mul_f32_e32 v3, v4, v3
	s_waitcnt lgkmcnt(0)
	v_sub_f32_e32 v4, v2, v6
	v_mul_f32_e32 v4, 0x3fb8aa3b, v4
	v_exp_f32_e32 v4, v4
	s_nop 0
	v_mul_f32_e32 v3, v3, v4
	ds_read_u16 v4, v185 offset:272
	s_waitcnt lgkmcnt(0)
	v_lshlrev_b32_e32 v4, 16, v4
	v_mul_f32_e32 v4, v5, v4
	v_sub_f32_e32 v5, v2, v7
	v_mul_f32_e32 v5, 0x3fb8aa3b, v5
	v_exp_f32_e32 v5, v5
	s_nop 0
	v_mul_f32_e32 v8, v4, v5
	ds_read_u16 v4, v185 offset:544
	s_waitcnt lgkmcnt(0)
	v_lshlrev_b32_e32 v6, 16, v4
	ds_read2_b32 v[4:5], v181 offset0:194 offset1:195
	s_waitcnt lgkmcnt(0)
	v_mul_f32_e32 v4, v4, v6
	ds_read2_b32 v[6:7], v181 offset0:2 offset1:3
	s_waitcnt lgkmcnt(0)
	v_sub_f32_e32 v6, v2, v6
	v_mul_f32_e32 v6, 0x3fb8aa3b, v6
	v_exp_f32_e32 v6, v6
	s_nop 0
	v_mul_f32_e32 v9, v4, v6
	ds_read_u16 v4, v185 offset:816
	s_waitcnt lgkmcnt(0)
	v_lshlrev_b32_e32 v4, 16, v4
	v_mul_f32_e32 v4, v5, v4
	v_sub_f32_e32 v5, v2, v7
	v_mul_f32_e32 v5, 0x3fb8aa3b, v5
	v_exp_f32_e32 v5, v5
	s_nop 0
	v_mul_f32_e32 v10, v4, v5
	ds_read_u16 v4, v185 offset:1088
	s_waitcnt lgkmcnt(0)
	v_lshlrev_b32_e32 v6, 16, v4
	ds_read2_b32 v[4:5], v181 offset0:196 offset1:197
	s_waitcnt lgkmcnt(0)
	v_mul_f32_e32 v4, v4, v6
	ds_read2_b32 v[6:7], v181 offset0:4 offset1:5
	s_waitcnt lgkmcnt(0)
	v_sub_f32_e32 v6, v2, v6
	v_mul_f32_e32 v6, 0x3fb8aa3b, v6
	v_exp_f32_e32 v6, v6
	s_nop 0
	v_mul_f32_e32 v11, v4, v6
	ds_read_u16 v4, v185 offset:1360
	s_waitcnt lgkmcnt(0)
	v_lshlrev_b32_e32 v4, 16, v4
	v_mul_f32_e32 v4, v5, v4
	v_sub_f32_e32 v5, v2, v7
	v_mul_f32_e32 v5, 0x3fb8aa3b, v5
	v_exp_f32_e32 v5, v5
	s_nop 0
	v_mul_f32_e32 v12, v4, v5
	ds_read_u16 v4, v185 offset:1632
	s_waitcnt lgkmcnt(0)
	v_lshlrev_b32_e32 v6, 16, v4
	ds_read2_b32 v[4:5], v181 offset0:198 offset1:199
	s_waitcnt lgkmcnt(0)
	v_mul_f32_e32 v4, v4, v6
	ds_read2_b32 v[6:7], v181 offset0:6 offset1:7
	s_waitcnt lgkmcnt(0)
	v_sub_f32_e32 v6, v2, v6
	v_mul_f32_e32 v6, 0x3fb8aa3b, v6
	v_exp_f32_e32 v6, v6
	s_nop 0
	v_mul_f32_e32 v13, v4, v6
	ds_read_u16 v4, v185 offset:1904
	v_cvt_pk_bf16_f32 v6, v11, v12
	s_waitcnt lgkmcnt(0)
	v_lshlrev_b32_e32 v4, 16, v4
	v_mul_f32_e32 v4, v5, v4
	v_sub_f32_e32 v5, v2, v7
	v_mul_f32_e32 v5, 0x3fb8aa3b, v5
	v_exp_f32_e32 v5, v5
	s_nop 0
	v_mul_f32_e32 v7, v4, v5
	v_cvt_pk_bf16_f32 v4, v3, v8
	v_cvt_pk_bf16_f32 v5, v9, v10
	v_cvt_pk_bf16_f32 v7, v13, v7
	ds_read_u16 v3, v185 offset:2176
	global_store_dwordx4 v[0:1], v[4:7], off offset:-32
	ds_read2_b32 v[4:5], v181 offset0:200 offset1:201
	ds_read2_b32 v[6:7], v181 offset0:8 offset1:9
	s_waitcnt lgkmcnt(0)
	v_lshlrev_b32_e32 v3, 16, v3
	s_waitcnt lgkmcnt(1)
	v_mul_f32_e32 v3, v4, v3
	s_waitcnt lgkmcnt(0)
	v_sub_f32_e32 v4, v2, v6
	v_mul_f32_e32 v4, 0x3fb8aa3b, v4
	v_exp_f32_e32 v4, v4
	s_nop 0
	v_mul_f32_e32 v3, v3, v4
	ds_read_u16 v4, v185 offset:2448
	s_waitcnt lgkmcnt(0)
	v_lshlrev_b32_e32 v4, 16, v4
	v_mul_f32_e32 v4, v5, v4
	v_sub_f32_e32 v5, v2, v7
	v_mul_f32_e32 v5, 0x3fb8aa3b, v5
	v_exp_f32_e32 v5, v5
	s_nop 0
	v_mul_f32_e32 v8, v4, v5
	ds_read_u16 v4, v185 offset:2720
	s_waitcnt lgkmcnt(0)
	v_lshlrev_b32_e32 v6, 16, v4
	ds_read2_b32 v[4:5], v181 offset0:202 offset1:203
	s_waitcnt lgkmcnt(0)
	v_mul_f32_e32 v4, v4, v6
	ds_read2_b32 v[6:7], v181 offset0:10 offset1:11
	s_waitcnt lgkmcnt(0)
	v_sub_f32_e32 v6, v2, v6
	v_mul_f32_e32 v6, 0x3fb8aa3b, v6
	v_exp_f32_e32 v6, v6
	s_nop 0
	v_mul_f32_e32 v9, v4, v6
	ds_read_u16 v4, v185 offset:2992
	s_waitcnt lgkmcnt(0)
	v_lshlrev_b32_e32 v4, 16, v4
	v_mul_f32_e32 v4, v5, v4
	v_sub_f32_e32 v5, v2, v7
	v_mul_f32_e32 v5, 0x3fb8aa3b, v5
	v_exp_f32_e32 v5, v5
	s_nop 0
	v_mul_f32_e32 v10, v4, v5
	ds_read_u16 v4, v185 offset:3264
	s_waitcnt lgkmcnt(0)
	v_lshlrev_b32_e32 v6, 16, v4
	ds_read2_b32 v[4:5], v181 offset0:204 offset1:205
	s_waitcnt lgkmcnt(0)
	v_mul_f32_e32 v4, v4, v6
	ds_read2_b32 v[6:7], v181 offset0:12 offset1:13
	s_waitcnt lgkmcnt(0)
	v_sub_f32_e32 v6, v2, v6
	v_mul_f32_e32 v6, 0x3fb8aa3b, v6
	v_exp_f32_e32 v6, v6
	s_nop 0
	v_mul_f32_e32 v11, v4, v6
	ds_read_u16 v4, v185 offset:3536
	s_waitcnt lgkmcnt(0)
	v_lshlrev_b32_e32 v4, 16, v4
	v_mul_f32_e32 v4, v5, v4
	v_sub_f32_e32 v5, v2, v7
	v_mul_f32_e32 v5, 0x3fb8aa3b, v5
	v_exp_f32_e32 v5, v5
	s_nop 0
	v_mul_f32_e32 v12, v4, v5
	ds_read_u16 v4, v185 offset:3808
	s_waitcnt lgkmcnt(0)
	v_lshlrev_b32_e32 v6, 16, v4
	ds_read2_b32 v[4:5], v181 offset0:206 offset1:207
	s_waitcnt lgkmcnt(0)
	v_mul_f32_e32 v4, v4, v6
	ds_read2_b32 v[6:7], v181 offset0:14 offset1:15
	s_waitcnt lgkmcnt(0)
	v_sub_f32_e32 v6, v2, v6
	v_mul_f32_e32 v6, 0x3fb8aa3b, v6
	v_exp_f32_e32 v6, v6
	s_nop 0
	v_mul_f32_e32 v13, v4, v6
	ds_read_u16 v4, v185 offset:4080
	v_cvt_pk_bf16_f32 v6, v11, v12
	s_waitcnt lgkmcnt(0)
	v_lshlrev_b32_e32 v4, 16, v4
	v_mul_f32_e32 v4, v5, v4
	v_sub_f32_e32 v5, v2, v7
	v_mul_f32_e32 v5, 0x3fb8aa3b, v5
	v_exp_f32_e32 v5, v5
	s_nop 0
	v_mul_f32_e32 v7, v4, v5
	v_cvt_pk_bf16_f32 v4, v3, v8
	v_cvt_pk_bf16_f32 v5, v9, v10
	v_cvt_pk_bf16_f32 v7, v13, v7
	ds_read_u16 v3, v185 offset:4352
	global_store_dwordx4 v[0:1], v[4:7], off offset:-16
	ds_read2_b32 v[4:5], v181 offset0:208 offset1:209
	ds_read2_b32 v[6:7], v181 offset0:16 offset1:17
	s_waitcnt lgkmcnt(0)
	v_lshlrev_b32_e32 v3, 16, v3
	s_waitcnt lgkmcnt(1)
	v_mul_f32_e32 v3, v4, v3
	s_waitcnt lgkmcnt(0)
	v_sub_f32_e32 v4, v2, v6
	v_mul_f32_e32 v4, 0x3fb8aa3b, v4
	v_exp_f32_e32 v4, v4
	s_nop 0
	v_mul_f32_e32 v3, v3, v4
	ds_read_u16 v4, v185 offset:4624
	s_waitcnt lgkmcnt(0)
	v_lshlrev_b32_e32 v4, 16, v4
	v_mul_f32_e32 v4, v5, v4
	v_sub_f32_e32 v5, v2, v7
	v_mul_f32_e32 v5, 0x3fb8aa3b, v5
	v_exp_f32_e32 v5, v5
	s_nop 0
	v_mul_f32_e32 v8, v4, v5
	ds_read_u16 v4, v185 offset:4896
	s_waitcnt lgkmcnt(0)
	v_lshlrev_b32_e32 v6, 16, v4
	ds_read2_b32 v[4:5], v181 offset0:210 offset1:211
	s_waitcnt lgkmcnt(0)
	v_mul_f32_e32 v4, v4, v6
	ds_read2_b32 v[6:7], v181 offset0:18 offset1:19
	s_waitcnt lgkmcnt(0)
	v_sub_f32_e32 v6, v2, v6
	v_mul_f32_e32 v6, 0x3fb8aa3b, v6
	v_exp_f32_e32 v6, v6
	s_nop 0
	v_mul_f32_e32 v9, v4, v6
	ds_read_u16 v4, v185 offset:5168
	s_waitcnt lgkmcnt(0)
	v_lshlrev_b32_e32 v4, 16, v4
	v_mul_f32_e32 v4, v5, v4
	v_sub_f32_e32 v5, v2, v7
	v_mul_f32_e32 v5, 0x3fb8aa3b, v5
	v_exp_f32_e32 v5, v5
	s_nop 0
	v_mul_f32_e32 v10, v4, v5
	ds_read_u16 v4, v185 offset:5440
	s_waitcnt lgkmcnt(0)
	v_lshlrev_b32_e32 v6, 16, v4
	ds_read2_b32 v[4:5], v181 offset0:212 offset1:213
	s_waitcnt lgkmcnt(0)
	v_mul_f32_e32 v4, v4, v6
	ds_read2_b32 v[6:7], v181 offset0:20 offset1:21
	s_waitcnt lgkmcnt(0)
	v_sub_f32_e32 v6, v2, v6
	v_mul_f32_e32 v6, 0x3fb8aa3b, v6
	v_exp_f32_e32 v6, v6
	s_nop 0
	v_mul_f32_e32 v11, v4, v6
	ds_read_u16 v4, v185 offset:5712
	s_waitcnt lgkmcnt(0)
	v_lshlrev_b32_e32 v4, 16, v4
	v_mul_f32_e32 v4, v5, v4
	v_sub_f32_e32 v5, v2, v7
	v_mul_f32_e32 v5, 0x3fb8aa3b, v5
	v_exp_f32_e32 v5, v5
	s_nop 0
	v_mul_f32_e32 v12, v4, v5
	ds_read_u16 v4, v185 offset:5984
	s_waitcnt lgkmcnt(0)
	v_lshlrev_b32_e32 v6, 16, v4
	ds_read2_b32 v[4:5], v181 offset0:214 offset1:215
	s_waitcnt lgkmcnt(0)
	v_mul_f32_e32 v4, v4, v6
	ds_read2_b32 v[6:7], v181 offset0:22 offset1:23
	s_waitcnt lgkmcnt(0)
	v_sub_f32_e32 v6, v2, v6
	v_mul_f32_e32 v6, 0x3fb8aa3b, v6
	v_exp_f32_e32 v6, v6
	s_nop 0
	v_mul_f32_e32 v13, v4, v6
	ds_read_u16 v4, v185 offset:6256
	v_cvt_pk_bf16_f32 v6, v11, v12
	s_waitcnt lgkmcnt(0)
	v_lshlrev_b32_e32 v4, 16, v4
	v_mul_f32_e32 v4, v5, v4
	v_sub_f32_e32 v5, v2, v7
	v_mul_f32_e32 v5, 0x3fb8aa3b, v5
	v_exp_f32_e32 v5, v5
	s_nop 0
	v_mul_f32_e32 v7, v4, v5
	v_cvt_pk_bf16_f32 v4, v3, v8
	v_cvt_pk_bf16_f32 v5, v9, v10
	v_cvt_pk_bf16_f32 v7, v13, v7
	ds_read_u16 v3, v185 offset:6528
	global_store_dwordx4 v[0:1], v[4:7], off
	ds_read2_b32 v[4:5], v181 offset0:216 offset1:217
	ds_read2_b32 v[6:7], v181 offset0:24 offset1:25
	s_waitcnt lgkmcnt(0)
	v_lshlrev_b32_e32 v3, 16, v3
	s_waitcnt lgkmcnt(1)
	v_mul_f32_e32 v3, v4, v3
	s_waitcnt lgkmcnt(0)
	v_sub_f32_e32 v4, v2, v6
	v_mul_f32_e32 v4, 0x3fb8aa3b, v4
	v_exp_f32_e32 v4, v4
	s_nop 0
	v_mul_f32_e32 v3, v3, v4
	ds_read_u16 v4, v185 offset:6800
	s_waitcnt lgkmcnt(0)
	v_lshlrev_b32_e32 v4, 16, v4
	v_mul_f32_e32 v4, v5, v4
	v_sub_f32_e32 v5, v2, v7
	v_mul_f32_e32 v5, 0x3fb8aa3b, v5
	v_exp_f32_e32 v5, v5
	s_nop 0
	v_mul_f32_e32 v8, v4, v5
	ds_read_u16 v4, v185 offset:7072
	s_waitcnt lgkmcnt(0)
	v_lshlrev_b32_e32 v6, 16, v4
	ds_read2_b32 v[4:5], v181 offset0:218 offset1:219
	s_waitcnt lgkmcnt(0)
	v_mul_f32_e32 v4, v4, v6
	ds_read2_b32 v[6:7], v181 offset0:26 offset1:27
	s_waitcnt lgkmcnt(0)
	v_sub_f32_e32 v6, v2, v6
	v_mul_f32_e32 v6, 0x3fb8aa3b, v6
	v_exp_f32_e32 v6, v6
	s_nop 0
	v_mul_f32_e32 v9, v4, v6
	ds_read_u16 v4, v185 offset:7344
	s_waitcnt lgkmcnt(0)
	v_lshlrev_b32_e32 v4, 16, v4
	v_mul_f32_e32 v4, v5, v4
	v_sub_f32_e32 v5, v2, v7
	v_mul_f32_e32 v5, 0x3fb8aa3b, v5
	v_exp_f32_e32 v5, v5
	s_nop 0
	v_mul_f32_e32 v10, v4, v5
	ds_read_u16 v4, v185 offset:7616
	s_waitcnt lgkmcnt(0)
	v_lshlrev_b32_e32 v6, 16, v4
	ds_read2_b32 v[4:5], v181 offset0:220 offset1:221
	s_waitcnt lgkmcnt(0)
	v_mul_f32_e32 v4, v4, v6
	ds_read2_b32 v[6:7], v181 offset0:28 offset1:29
	s_waitcnt lgkmcnt(0)
	v_sub_f32_e32 v6, v2, v6
	v_mul_f32_e32 v6, 0x3fb8aa3b, v6
	v_exp_f32_e32 v6, v6
	s_nop 0
	v_mul_f32_e32 v11, v4, v6
	ds_read_u16 v4, v185 offset:7888
	s_waitcnt lgkmcnt(0)
	v_lshlrev_b32_e32 v4, 16, v4
	v_mul_f32_e32 v4, v5, v4
	v_sub_f32_e32 v5, v2, v7
	v_mul_f32_e32 v5, 0x3fb8aa3b, v5
	v_exp_f32_e32 v5, v5
	s_nop 0
	v_mul_f32_e32 v12, v4, v5
	ds_read_u16 v4, v185 offset:8160
	s_waitcnt lgkmcnt(0)
	v_lshlrev_b32_e32 v6, 16, v4
	ds_read2_b32 v[4:5], v181 offset0:222 offset1:223
	s_waitcnt lgkmcnt(0)
	v_mul_f32_e32 v4, v4, v6
	ds_read2_b32 v[6:7], v181 offset0:30 offset1:31
	s_waitcnt lgkmcnt(0)
	v_sub_f32_e32 v6, v2, v6
	v_mul_f32_e32 v6, 0x3fb8aa3b, v6
	v_exp_f32_e32 v6, v6
	s_nop 0
	v_mul_f32_e32 v13, v4, v6
	ds_read_u16 v4, v185 offset:8432
	v_cvt_pk_bf16_f32 v6, v11, v12
	s_waitcnt lgkmcnt(0)
	v_lshlrev_b32_e32 v4, 16, v4
	v_mul_f32_e32 v4, v5, v4
	v_sub_f32_e32 v5, v2, v7
	v_mul_f32_e32 v5, 0x3fb8aa3b, v5
	v_exp_f32_e32 v5, v5
	s_nop 0
	v_mul_f32_e32 v7, v4, v5
	v_cvt_pk_bf16_f32 v4, v3, v8
	v_cvt_pk_bf16_f32 v5, v9, v10
	v_cvt_pk_bf16_f32 v7, v13, v7
	global_store_dwordx4 v[0:1], v[4:7], off offset:16
	s_and_saveexec_b64 s[44:45], s[10:11]
	s_cbranch_execz .LBB0_359
	s_lshl_b64 vcc, s[40:41], 2
	v_mul_f32_e32 v0, 0x3fb8aa3b, v2
	s_add_u32 s36, s68, vcc_lo
	v_exp_f32_e32 v0, v0
	s_addc_u32 s37, s82, vcc_hi
	s_add_u32 vcc_lo, s74, s36
	s_addc_u32 vcc_hi, s75, s37
	global_store_dword v145, v0, vcc
